# norm_rows<1>: second wave reduction (sum of squares of x) by DPP row reduction + v_readlane instead of six ds_bpermute hops, on v58
# speedup vs baseline: 1.0058x; 1.0042x over previous
; __device__ __forceinline__ float bflo(unsigned w) { return __uint_as_float(w << 16); }
; __device__ __forceinline__ float bfhi(unsigned w) { return __uint_as_float(w & 0xffff0000u); }
; template <int MODE> ...
;     ...
;             const bf16* pr = xn + (size_t)row * DM; bf16* pw_out = xn_out + (size_t)row * DM; const bf16* hr = hb + (size_t)row * DM;
;             v2u pw[16], hw[16]; float ss = 0.f;
; #pragma unroll
;             for (int j = 0; j < 16; ++j) { pw[j] = *(const v2u*)(pr + lo4 + 256 * j); hw[j] = *(const v2u*)(hr + lo4 + 256 * j); }
;             const float ri = 1.f / rs[row];
; #pragma unroll
;             for (int j = 0; j < 16; ++j) { const float a = bflo(hw[j].x), b = bfhi(hw[j].x), c = bflo(hw[j].y), d = bfhi(hw[j].y); ss += a * a + b * b + c * c + d * d; }
.LBB0_776:
	v_lshl_add_u64 v[66:67], v[0:1], 0, s[12:13]
	v_add_co_u32_e32 v36, vcc, 0x3000000, v66
	s_mov_b64 s[6:7], vcc
	v_add_co_u32_e32 v2, vcc, 0x7000000, v66
	s_add_u32 s62, s64, s12
	s_nop 0
	v_addc_co_u32_e32 v3, vcc, 0, v67, vcc
	global_load_dwordx2 v[60:61], v[2:3], off
	global_load_dwordx2 v[54:55], v[2:3], off offset:512
	global_load_dwordx2 v[52:53], v[2:3], off offset:1024
	global_load_dwordx2 v[48:49], v[2:3], off offset:1536
	global_load_dwordx2 v[44:45], v[2:3], off offset:2048
	global_load_dwordx2 v[42:43], v[2:3], off offset:2560
	v_add_co_u32_e32 v4, vcc, s39, v66
	s_addc_u32 s63, s65, s13
	s_nop 0
	v_addc_co_u32_e32 v5, vcc, 0, v67, vcc
	v_add_co_u32_e32 v40, vcc, s41, v66
	s_waitcnt vmcnt(5)
	v_and_b32_e32 v69, 0xffff0000, v60
	v_addc_co_u32_e32 v41, vcc, 0, v67, vcc
	v_addc_co_u32_e64 v37, vcc, 0, v67, s[6:7]
	global_load_dwordx2 v[38:39], v[2:3], off offset:3072
	global_load_dwordx2 v[30:31], v[4:5], off
	global_load_dwordx2 v[26:27], v[4:5], off offset:512
	global_load_dwordx2 v[22:23], v[4:5], off offset:1024
	global_load_dwordx2 v[18:19], v[4:5], off offset:1536
	global_load_dwordx2 v[32:33], v[40:41], off
	global_load_dwordx2 v[28:29], v[40:41], off offset:512
	global_load_dwordx2 v[24:25], v[40:41], off offset:1024
	global_load_dwordx2 v[20:21], v[40:41], off offset:1536
	global_load_dwordx2 v[34:35], v[2:3], off offset:3584
	global_load_dwordx2 v[14:15], v[4:5], off offset:2048
	global_load_dwordx2 v[10:11], v[4:5], off offset:2560
	global_load_dwordx2 v[6:7], v[4:5], off offset:3072
	s_nop 0
	global_load_dwordx2 v[2:3], v[4:5], off offset:3584
	global_load_dwordx2 v[16:17], v[40:41], off offset:2048
	global_load_dwordx2 v[12:13], v[40:41], off offset:2560
	global_load_dwordx2 v[8:9], v[40:41], off offset:3072
	s_nop 0
	global_load_dwordx2 v[4:5], v[40:41], off offset:3584
	global_load_dword v78, v98, s[62:63]
	global_load_dwordx2 v[64:65], v[36:37], off
	global_load_dwordx2 v[62:63], v[36:37], off offset:512
	global_load_dwordx2 v[58:59], v[36:37], off offset:1024
	global_load_dwordx2 v[56:57], v[36:37], off offset:1536
	global_load_dwordx2 v[50:51], v[36:37], off offset:2048
	global_load_dwordx2 v[46:47], v[36:37], off offset:2560
	global_load_dwordx2 v[40:41], v[36:37], off offset:3072
	s_nop 0
	global_load_dwordx2 v[36:37], v[36:37], off offset:3584
	s_waitcnt vmcnt(31)
	v_and_b32_e32 v74, 0xffff0000, v54
	v_lshlrev_b32_e32 v68, 16, v60
	v_lshlrev_b32_e32 v73, 16, v54
	v_mul_f32_e32 v69, v69, v69
	v_mul_f32_e32 v74, v74, v74
	v_lshlrev_b32_e32 v70, 16, v61
	v_lshlrev_b32_e32 v75, 16, v55
	s_waitcnt vmcnt(30)
	v_and_b32_e32 v79, 0xffff0000, v52
	v_fmac_f32_e32 v69, v68, v68
	v_fmac_f32_e32 v74, v73, v73
	v_and_b32_e32 v72, 0xffff0000, v61
	v_and_b32_e32 v76, 0xffff0000, v55
	v_lshlrev_b32_e32 v77, 16, v52
	s_waitcnt vmcnt(29)
	v_and_b32_e32 v83, 0xffff0000, v48
	s_waitcnt vmcnt(28)
	v_and_b32_e32 v87, 0xffff0000, v44
	v_mul_f32_e32 v79, v79, v79
	v_fmac_f32_e32 v69, v70, v70
	v_fmac_f32_e32 v74, v75, v75
	v_lshlrev_b32_e32 v80, 16, v53
	v_lshlrev_b32_e32 v82, 16, v48
	v_lshlrev_b32_e32 v86, 16, v44
	v_mul_f32_e32 v83, v83, v83
	v_fmac_f32_e32 v79, v77, v77
	v_fmac_f32_e32 v69, v72, v72
	v_fmac_f32_e32 v74, v76, v76
	v_mul_f32_e32 v72, v87, v87
	v_and_b32_e32 v81, 0xffff0000, v53
	v_lshlrev_b32_e32 v84, 16, v49
	v_fmac_f32_e32 v83, v82, v82
	v_fmac_f32_e32 v79, v80, v80
	v_add_f32_e32 v68, v69, v74
	v_lshlrev_b32_e32 v69, 16, v45
	v_fmac_f32_e32 v72, v86, v86
	v_and_b32_e32 v85, 0xffff0000, v49
	v_fmac_f32_e32 v83, v84, v84
	v_fmac_f32_e32 v79, v81, v81
	v_and_b32_e32 v70, 0xffff0000, v45
	v_fmac_f32_e32 v72, v69, v69
	v_fmac_f32_e32 v83, v85, v85
	v_add_f32_e32 v68, v68, v79
	v_fmac_f32_e32 v72, v70, v70
	s_waitcnt vmcnt(27)
	v_and_b32_e32 v70, 0xffff0000, v42
	v_add_f32_e32 v68, v68, v83
	v_lshlrev_b32_e32 v69, 16, v42
	v_mul_f32_e32 v70, v70, v70
	v_add_f32_e32 v68, v68, v72
	v_lshlrev_b32_e32 v72, 16, v43
	v_fmac_f32_e32 v70, v69, v69
	v_and_b32_e32 v73, 0xffff0000, v43
	v_fmac_f32_e32 v70, v72, v72
	v_fmac_f32_e32 v70, v73, v73
	v_add_f32_e32 v68, v68, v70
	s_waitcnt vmcnt(26)
	v_and_b32_e32 v70, 0xffff0000, v38
	v_lshlrev_b32_e32 v69, 16, v38
	v_mul_f32_e32 v70, v70, v70
	v_lshlrev_b32_e32 v72, 16, v39
	v_fmac_f32_e32 v70, v69, v69
	v_and_b32_e32 v73, 0xffff0000, v39
	v_fmac_f32_e32 v70, v72, v72
	v_fmac_f32_e32 v70, v73, v73
	v_add_f32_e32 v68, v68, v70
	s_waitcnt vmcnt(17)
	v_and_b32_e32 v70, 0xffff0000, v34
	v_lshlrev_b32_e32 v69, 16, v34
	v_mul_f32_e32 v70, v70, v70
	v_lshlrev_b32_e32 v72, 16, v35
	v_fmac_f32_e32 v70, v69, v69
	v_and_b32_e32 v73, 0xffff0000, v35
	v_fmac_f32_e32 v70, v72, v72
	v_fmac_f32_e32 v70, v73, v73
	v_add_f32_e32 v68, v68, v70
	v_and_b32_e32 v70, 0xffff0000, v32
	v_lshlrev_b32_e32 v69, 16, v32
	v_mul_f32_e32 v70, v70, v70
	v_lshlrev_b32_e32 v72, 16, v33
	v_fmac_f32_e32 v70, v69, v69
	v_and_b32_e32 v73, 0xffff0000, v33
	v_fmac_f32_e32 v70, v72, v72
	v_fmac_f32_e32 v70, v73, v73
	v_add_f32_e32 v68, v68, v70
	v_and_b32_e32 v70, 0xffff0000, v28
	v_lshlrev_b32_e32 v69, 16, v28
	v_mul_f32_e32 v70, v70, v70
	v_lshlrev_b32_e32 v72, 16, v29
	v_fmac_f32_e32 v70, v69, v69
	v_and_b32_e32 v73, 0xffff0000, v29
	v_fmac_f32_e32 v70, v72, v72
	v_fmac_f32_e32 v70, v73, v73
	v_add_f32_e32 v68, v68, v70
	v_and_b32_e32 v70, 0xffff0000, v24
	v_lshlrev_b32_e32 v69, 16, v24
	v_mul_f32_e32 v70, v70, v70
	v_lshlrev_b32_e32 v72, 16, v25
	v_fmac_f32_e32 v70, v69, v69
	v_and_b32_e32 v73, 0xffff0000, v25
	v_fmac_f32_e32 v70, v72, v72
	v_fmac_f32_e32 v70, v73, v73
	v_add_f32_e32 v68, v68, v70
	v_and_b32_e32 v70, 0xffff0000, v20
	v_lshlrev_b32_e32 v69, 16, v20
	v_mul_f32_e32 v70, v70, v70
	v_lshlrev_b32_e32 v72, 16, v21
	v_fmac_f32_e32 v70, v69, v69
	v_and_b32_e32 v73, 0xffff0000, v21
	v_fmac_f32_e32 v70, v72, v72
	v_fmac_f32_e32 v70, v73, v73
	s_waitcnt vmcnt(11)
; #define LAS __attribute__((address_space(3)))
; __device__ __forceinline__ float bflo(unsigned w) { return __uint_as_float(w << 16); }
; __device__ __forceinline__ float bfhi(unsigned w) { return __uint_as_float(w & 0xffff0000u); }
; #define LAUNDER_ROW(pw, hw) do { LAUNDER8(pw, 0); LAUNDER8(pw, 8); LAUNDER8(hw, 0); LAUNDER8(hw, 8); } while (0)
; template <int MODE> ...
;     ...
;             const float ri = 1.f / rs[row];
; #pragma unroll
;             for (int j = 0; j < 16; ++j) { const float a = bflo(hw[j].x), b = bfhi(hw[j].x), c = bflo(hw[j].y), d = bfhi(hw[j].y); ss += a * a + b * b + c * c + d * d; }
;             const float rstd = rsqrtf(wave_sum(ss) * (1.f / DM) + EPS);
;             asm volatile("" ::: "memory");
;             LAUNDER_ROW(pw, hw);
;             float ss2 = 0.f;
; #pragma unroll
;             for (int j = 0; j < 16; ++j) { const f32x4 g = *(const LAS f32x4*)(GP + lo4 + 256 * j), gi = *(const LAS f32x4*)(GI + lo4 + 256 * j);
;                 f32x4 x;
;                 x.x = bflo(pw[j].x) * ri * gi.x + bflo(hw[j].x) * rstd * g.x; x.y = bfhi(pw[j].x) * ri * gi.y + bfhi(hw[j].x) * rstd * g.y;
;                 x.z = bflo(pw[j].y) * ri * gi.z + bflo(hw[j].y) * rstd * g.z; x.w = bfhi(pw[j].y) * ri * gi.w + bfhi(hw[j].y) * rstd * g.w;
;                 if (MODE == 2) *(f32x4*)(xout + (size_t)row * DM + lo4 + 256 * j) = x;
;                 else ss2 += x.x * x.x + x.y * x.y + x.z * x.z + x.w * x.w;
	v_and_b32_e32 v73, 0xffff0000, v12
	v_and_b32_e32 v72, 0xffff0000, v16
	v_add_f32_e32 v70, v68, v70
	v_lshlrev_b32_e32 v69, 16, v12
	v_lshlrev_b32_e32 v68, 16, v16
	v_pk_mul_f32 v[72:73], v[72:73], v[72:73]
	v_lshlrev_b32_e32 v75, 16, v13
	v_lshlrev_b32_e32 v74, 16, v17
	v_pk_fma_f32 v[68:69], v[68:69], v[68:69], v[72:73]
	v_and_b32_e32 v77, 0xffff0000, v13
	v_and_b32_e32 v76, 0xffff0000, v17
	v_pk_fma_f32 v[68:69], v[74:75], v[74:75], v[68:69]
	s_waitcnt vmcnt(9)
	v_and_b32_e32 v73, 0xffff0000, v4
	v_pk_fma_f32 v[68:69], v[76:77], v[76:77], v[68:69]
	v_and_b32_e32 v72, 0xffff0000, v8
	v_add_f32_e32 v68, v70, v68
	v_add_f32_e32 v70, v68, v69
	v_lshlrev_b32_e32 v69, 16, v4
	v_lshlrev_b32_e32 v68, 16, v8
	v_pk_mul_f32 v[72:73], v[72:73], v[72:73]
	v_lshlrev_b32_e32 v75, 16, v5
	v_lshlrev_b32_e32 v74, 16, v9
	v_pk_fma_f32 v[68:69], v[68:69], v[68:69], v[72:73]
	v_and_b32_e32 v77, 0xffff0000, v5
	v_and_b32_e32 v76, 0xffff0000, v9
	v_pk_fma_f32 v[68:69], v[74:75], v[74:75], v[68:69]
	s_waitcnt vmcnt(0)
	v_pk_fma_f32 v[68:69], v[76:77], v[76:77], v[68:69]
	v_div_scale_f32 v77, s[6:7], v78, v78, 1.0
	v_add_f32_e32 v68, v70, v68
	v_add_f32_e32 v68, v68, v69
	v_and_b32_e32 v69, 64, v100
	v_add_u32_e32 v69, 64, v69
	v_xor_b32_e32 v70, 1, v100
	v_cmp_lt_i32_e32 vcc, v70, v69
	v_rcp_f32_e32 v79, v77
	v_lshlrev_b32_e32 v86, 16, v60
	v_cndmask_b32_e32 v70, v100, v70, vcc
	v_lshlrev_b32_e32 v70, 2, v70
	ds_bpermute_b32 v72, v70, v68
	v_fma_f32 v80, -v77, v79, 1.0
	v_fmac_f32_e32 v79, v80, v79
	s_waitcnt lgkmcnt(0)
	v_add_f32_e32 v68, v68, v72
	v_xor_b32_e32 v72, 2, v100
	v_cmp_lt_i32_e32 vcc, v72, v69
	s_nop 1
	v_cndmask_b32_e32 v72, v100, v72, vcc
	v_lshlrev_b32_e32 v72, 2, v72
	ds_bpermute_b32 v73, v72, v68
	s_waitcnt lgkmcnt(0)
	v_add_f32_e32 v68, v68, v73
	v_xor_b32_e32 v73, 4, v100
	v_cmp_lt_i32_e32 vcc, v73, v69
	s_nop 1
	v_cndmask_b32_e32 v73, v100, v73, vcc
	v_lshlrev_b32_e32 v73, 2, v73
	ds_bpermute_b32 v74, v73, v68
	s_waitcnt lgkmcnt(0)
	v_add_f32_e32 v68, v68, v74
	v_xor_b32_e32 v74, 8, v100
	v_cmp_lt_i32_e32 vcc, v74, v69
	s_nop 1
	v_cndmask_b32_e32 v74, v100, v74, vcc
	v_lshlrev_b32_e32 v74, 2, v74
	ds_bpermute_b32 v75, v74, v68
	s_waitcnt lgkmcnt(0)
	v_add_f32_e32 v68, v68, v75
	v_xor_b32_e32 v75, 16, v100
	v_cmp_lt_i32_e32 vcc, v75, v69
	s_nop 1
	v_cndmask_b32_e32 v75, v100, v75, vcc
	v_lshlrev_b32_e32 v75, 2, v75
	ds_bpermute_b32 v76, v75, v68
	v_div_scale_f32 v80, vcc, 1.0, v78, 1.0
	v_mul_f32_e32 v81, v80, v79
	v_fma_f32 v82, -v77, v81, v80
	s_waitcnt lgkmcnt(0)
	v_add_f32_e32 v68, v68, v76
	v_xor_b32_e32 v76, 32, v100
	v_cmp_lt_i32_e64 s[6:7], v76, v69
	v_fmac_f32_e32 v81, v82, v79
	v_fma_f32 v77, -v77, v81, v80
	v_cndmask_b32_e64 v69, v100, v76, s[6:7]
	v_lshlrev_b32_e32 v76, 2, v69
	ds_bpermute_b32 v69, v76, v68
	s_waitcnt lgkmcnt(0)
	v_add_f32_e32 v68, v68, v69
	v_fmamk_f32 v68, v68, 0x39800000, v99
	v_mul_f32_e32 v69, 0x4b800000, v68
	v_cmp_gt_f32_e64 s[6:7], s66, v68
	s_nop 1
	v_cndmask_b32_e64 v68, v68, v69, s[6:7]
	v_rsq_f32_e32 v69, v68
	v_div_fmas_f32 v68, v77, v79, v81
	v_div_fixup_f32 v68, v68, v78, 1.0
	v_mul_f32_e32 v77, 0x45800000, v69
	v_cndmask_b32_e64 v69, v69, v77, s[6:7]
	v_mov_b32_e32 v228, v68
	v_mov_b32_e32 v229, v68
	v_mov_b32_e32 v230, v69
	v_mov_b32_e32 v231, v69
	ds_read_b128 v[196:199], v71
	ds_read_b128 v[200:203], v71 offset:32768
	ds_read_b128 v[204:207], v71 offset:1024
	ds_read_b128 v[208:211], v71 offset:33792
	v_lshlrev_b32_e32 v212, 16, v64
	v_and_b32_e32 v213, 0xffff0000, v64
	v_lshlrev_b32_e32 v214, 16, v65
	v_and_b32_e32 v215, 0xffff0000, v65
	v_lshlrev_b32_e32 v216, 16, v60
	v_and_b32_e32 v217, 0xffff0000, v60
	v_lshlrev_b32_e32 v218, 16, v61
	v_and_b32_e32 v219, 0xffff0000, v61
	v_pk_mul_f32 v[212:213], v[228:229], v[212:213]
	v_pk_mul_f32 v[214:215], v[228:229], v[214:215]
	v_pk_mul_f32 v[216:217], v[230:231], v[216:217]
	v_pk_mul_f32 v[218:219], v[230:231], v[218:219]
	s_waitcnt lgkmcnt(2)
	v_pk_mul_f32 v[132:133], v[212:213], v[200:201]
	v_pk_mul_f32 v[134:135], v[214:215], v[202:203]
	v_pk_fma_f32 v[132:133], v[196:197], v[216:217], v[132:133]
	v_pk_fma_f32 v[134:135], v[198:199], v[218:219], v[134:135]
	v_pk_mul_f32 v[234:235], v[132:133], v[132:133]
	v_pk_fma_f32 v[234:235], v[134:135], v[134:135], v[234:235]
	ds_read_b128 v[196:199], v71 offset:2048
	ds_read_b128 v[200:203], v71 offset:34816
	v_lshlrev_b32_e32 v212, 16, v62
	v_and_b32_e32 v213, 0xffff0000, v62
	v_lshlrev_b32_e32 v214, 16, v63
	v_and_b32_e32 v215, 0xffff0000, v63
	v_lshlrev_b32_e32 v216, 16, v54
	v_and_b32_e32 v217, 0xffff0000, v54
	v_lshlrev_b32_e32 v218, 16, v55
	v_and_b32_e32 v219, 0xffff0000, v55
	v_pk_mul_f32 v[212:213], v[228:229], v[212:213]
	v_pk_mul_f32 v[214:215], v[228:229], v[214:215]
	v_pk_mul_f32 v[216:217], v[230:231], v[216:217]
	v_pk_mul_f32 v[218:219], v[230:231], v[218:219]
	s_waitcnt lgkmcnt(2)
	v_pk_mul_f32 v[136:137], v[212:213], v[208:209]
	v_pk_mul_f32 v[138:139], v[214:215], v[210:211]
	v_pk_fma_f32 v[136:137], v[204:205], v[216:217], v[136:137]
	v_pk_fma_f32 v[138:139], v[206:207], v[218:219], v[138:139]
	v_pk_fma_f32 v[234:235], v[136:137], v[136:137], v[234:235]
	v_pk_fma_f32 v[234:235], v[138:139], v[138:139], v[234:235]
	ds_read_b128 v[204:207], v71 offset:3072
	ds_read_b128 v[208:211], v71 offset:35840
	v_lshlrev_b32_e32 v212, 16, v58
	v_and_b32_e32 v213, 0xffff0000, v58
	v_lshlrev_b32_e32 v214, 16, v59
	v_and_b32_e32 v215, 0xffff0000, v59
	v_lshlrev_b32_e32 v216, 16, v52
	v_and_b32_e32 v217, 0xffff0000, v52
	v_lshlrev_b32_e32 v218, 16, v53
	v_and_b32_e32 v219, 0xffff0000, v53
	v_pk_mul_f32 v[212:213], v[228:229], v[212:213]
	v_pk_mul_f32 v[214:215], v[228:229], v[214:215]
	v_pk_mul_f32 v[216:217], v[230:231], v[216:217]
	v_pk_mul_f32 v[218:219], v[230:231], v[218:219]
	s_waitcnt lgkmcnt(2)
; #define LAS __attribute__((address_space(3)))
; __device__ __forceinline__ float bflo(unsigned w) { return __uint_as_float(w << 16); }
; __device__ __forceinline__ float bfhi(unsigned w) { return __uint_as_float(w & 0xffff0000u); }
; template <int MODE> ...
;     ...
;             for (int j = 0; j < 16; ++j) { const f32x4 g = *(const LAS f32x4*)(GP + lo4 + 256 * j), gi = *(const LAS f32x4*)(GI + lo4 + 256 * j);
;                 f32x4 x;
;                 x.x = bflo(pw[j].x) * ri * gi.x + bflo(hw[j].x) * rstd * g.x; x.y = bfhi(pw[j].x) * ri * gi.y + bfhi(hw[j].x) * rstd * g.y;
;                 x.z = bflo(pw[j].y) * ri * gi.z + bflo(hw[j].y) * rstd * g.z; x.w = bfhi(pw[j].y) * ri * gi.w + bfhi(hw[j].y) * rstd * g.w;
;                 if (MODE == 2) *(f32x4*)(xout + (size_t)row * DM + lo4 + 256 * j) = x;
;                 else ss2 += x.x * x.x + x.y * x.y + x.z * x.z + x.w * x.w;
;                 if (j & 1) __builtin_amdgcn_sched_barrier(0); }
	v_pk_mul_f32 v[140:141], v[212:213], v[200:201]
	v_pk_mul_f32 v[142:143], v[214:215], v[202:203]
	v_pk_fma_f32 v[140:141], v[196:197], v[216:217], v[140:141]
	v_pk_fma_f32 v[142:143], v[198:199], v[218:219], v[142:143]
	v_pk_fma_f32 v[234:235], v[140:141], v[140:141], v[234:235]
	v_pk_fma_f32 v[234:235], v[142:143], v[142:143], v[234:235]
	ds_read_b128 v[196:199], v71 offset:4096
	ds_read_b128 v[200:203], v71 offset:36864
	v_lshlrev_b32_e32 v212, 16, v56
	v_and_b32_e32 v213, 0xffff0000, v56
	v_lshlrev_b32_e32 v214, 16, v57
	v_and_b32_e32 v215, 0xffff0000, v57
	v_lshlrev_b32_e32 v216, 16, v48
	v_and_b32_e32 v217, 0xffff0000, v48
	v_lshlrev_b32_e32 v218, 16, v49
	v_and_b32_e32 v219, 0xffff0000, v49
	v_pk_mul_f32 v[212:213], v[228:229], v[212:213]
	v_pk_mul_f32 v[214:215], v[228:229], v[214:215]
	v_pk_mul_f32 v[216:217], v[230:231], v[216:217]
	v_pk_mul_f32 v[218:219], v[230:231], v[218:219]
	s_waitcnt lgkmcnt(2)
	v_pk_mul_f32 v[144:145], v[212:213], v[208:209]
	v_pk_mul_f32 v[146:147], v[214:215], v[210:211]
	v_pk_fma_f32 v[144:145], v[204:205], v[216:217], v[144:145]
	v_pk_fma_f32 v[146:147], v[206:207], v[218:219], v[146:147]
	v_pk_fma_f32 v[234:235], v[144:145], v[144:145], v[234:235]
	v_pk_fma_f32 v[234:235], v[146:147], v[146:147], v[234:235]
	ds_read_b128 v[204:207], v71 offset:5120
	ds_read_b128 v[208:211], v71 offset:37888
	v_lshlrev_b32_e32 v212, 16, v50
	v_and_b32_e32 v213, 0xffff0000, v50
	v_lshlrev_b32_e32 v214, 16, v51
	v_and_b32_e32 v215, 0xffff0000, v51
	v_lshlrev_b32_e32 v216, 16, v44
	v_and_b32_e32 v217, 0xffff0000, v44
	v_lshlrev_b32_e32 v218, 16, v45
	v_and_b32_e32 v219, 0xffff0000, v45
	v_pk_mul_f32 v[212:213], v[228:229], v[212:213]
	v_pk_mul_f32 v[214:215], v[228:229], v[214:215]
	v_pk_mul_f32 v[216:217], v[230:231], v[216:217]
	v_pk_mul_f32 v[218:219], v[230:231], v[218:219]
	s_waitcnt lgkmcnt(2)
	v_pk_mul_f32 v[148:149], v[212:213], v[200:201]
	v_pk_mul_f32 v[150:151], v[214:215], v[202:203]
	v_pk_fma_f32 v[148:149], v[196:197], v[216:217], v[148:149]
	v_pk_fma_f32 v[150:151], v[198:199], v[218:219], v[150:151]
	v_pk_fma_f32 v[234:235], v[148:149], v[148:149], v[234:235]
	v_pk_fma_f32 v[234:235], v[150:151], v[150:151], v[234:235]
	ds_read_b128 v[196:199], v71 offset:6144
	ds_read_b128 v[200:203], v71 offset:38912
	v_lshlrev_b32_e32 v212, 16, v46
	v_and_b32_e32 v213, 0xffff0000, v46
	v_lshlrev_b32_e32 v214, 16, v47
	v_and_b32_e32 v215, 0xffff0000, v47
	v_lshlrev_b32_e32 v216, 16, v42
	v_and_b32_e32 v217, 0xffff0000, v42
	v_lshlrev_b32_e32 v218, 16, v43
	v_and_b32_e32 v219, 0xffff0000, v43
	v_pk_mul_f32 v[212:213], v[228:229], v[212:213]
	v_pk_mul_f32 v[214:215], v[228:229], v[214:215]
	v_pk_mul_f32 v[216:217], v[230:231], v[216:217]
	v_pk_mul_f32 v[218:219], v[230:231], v[218:219]
	s_waitcnt lgkmcnt(2)
	v_pk_mul_f32 v[152:153], v[212:213], v[208:209]
	v_pk_mul_f32 v[154:155], v[214:215], v[210:211]
	v_pk_fma_f32 v[152:153], v[204:205], v[216:217], v[152:153]
	v_pk_fma_f32 v[154:155], v[206:207], v[218:219], v[154:155]
	v_pk_fma_f32 v[234:235], v[152:153], v[152:153], v[234:235]
	v_pk_fma_f32 v[234:235], v[154:155], v[154:155], v[234:235]
	ds_read_b128 v[204:207], v71 offset:7168
	ds_read_b128 v[208:211], v71 offset:39936
	v_lshlrev_b32_e32 v212, 16, v40
	v_and_b32_e32 v213, 0xffff0000, v40
	v_lshlrev_b32_e32 v214, 16, v41
	v_and_b32_e32 v215, 0xffff0000, v41
	v_lshlrev_b32_e32 v216, 16, v38
	v_and_b32_e32 v217, 0xffff0000, v38
	v_lshlrev_b32_e32 v218, 16, v39
	v_and_b32_e32 v219, 0xffff0000, v39
	v_pk_mul_f32 v[212:213], v[228:229], v[212:213]
	v_pk_mul_f32 v[214:215], v[228:229], v[214:215]
	v_pk_mul_f32 v[216:217], v[230:231], v[216:217]
	v_pk_mul_f32 v[218:219], v[230:231], v[218:219]
	s_waitcnt lgkmcnt(2)
	v_pk_mul_f32 v[156:157], v[212:213], v[200:201]
	v_pk_mul_f32 v[158:159], v[214:215], v[202:203]
	v_pk_fma_f32 v[156:157], v[196:197], v[216:217], v[156:157]
	v_pk_fma_f32 v[158:159], v[198:199], v[218:219], v[158:159]
	v_pk_fma_f32 v[234:235], v[156:157], v[156:157], v[234:235]
	v_pk_fma_f32 v[234:235], v[158:159], v[158:159], v[234:235]
	ds_read_b128 v[196:199], v71 offset:8192
	ds_read_b128 v[200:203], v71 offset:40960
	v_lshlrev_b32_e32 v212, 16, v36
	v_and_b32_e32 v213, 0xffff0000, v36
	v_lshlrev_b32_e32 v214, 16, v37
	v_and_b32_e32 v215, 0xffff0000, v37
	v_lshlrev_b32_e32 v216, 16, v34
	v_and_b32_e32 v217, 0xffff0000, v34
	v_lshlrev_b32_e32 v218, 16, v35
	v_and_b32_e32 v219, 0xffff0000, v35
	v_pk_mul_f32 v[212:213], v[228:229], v[212:213]
	v_pk_mul_f32 v[214:215], v[228:229], v[214:215]
	v_pk_mul_f32 v[216:217], v[230:231], v[216:217]
	v_pk_mul_f32 v[218:219], v[230:231], v[218:219]
	s_waitcnt lgkmcnt(2)
	v_pk_mul_f32 v[160:161], v[212:213], v[208:209]
	v_pk_mul_f32 v[162:163], v[214:215], v[210:211]
	v_pk_fma_f32 v[160:161], v[204:205], v[216:217], v[160:161]
	v_pk_fma_f32 v[162:163], v[206:207], v[218:219], v[162:163]
	v_pk_fma_f32 v[234:235], v[160:161], v[160:161], v[234:235]
	v_pk_fma_f32 v[234:235], v[162:163], v[162:163], v[234:235]
	ds_read_b128 v[204:207], v71 offset:9216
	ds_read_b128 v[208:211], v71 offset:41984
	v_lshlrev_b32_e32 v212, 16, v30
	v_and_b32_e32 v213, 0xffff0000, v30
	v_lshlrev_b32_e32 v214, 16, v31
	v_and_b32_e32 v215, 0xffff0000, v31
	v_lshlrev_b32_e32 v216, 16, v32
	v_and_b32_e32 v217, 0xffff0000, v32
	v_lshlrev_b32_e32 v218, 16, v33
	v_and_b32_e32 v219, 0xffff0000, v33
	v_pk_mul_f32 v[212:213], v[228:229], v[212:213]
	v_pk_mul_f32 v[214:215], v[228:229], v[214:215]
	v_pk_mul_f32 v[216:217], v[230:231], v[216:217]
	v_pk_mul_f32 v[218:219], v[230:231], v[218:219]
	s_waitcnt lgkmcnt(2)
; #define LAS __attribute__((address_space(3)))
; __device__ __forceinline__ float bflo(unsigned w) { return __uint_as_float(w << 16); }
; __device__ __forceinline__ float bfhi(unsigned w) { return __uint_as_float(w & 0xffff0000u); }
; template <int MODE> ...
;     ...
;             for (int j = 0; j < 16; ++j) { const f32x4 g = *(const LAS f32x4*)(GP + lo4 + 256 * j), gi = *(const LAS f32x4*)(GI + lo4 + 256 * j);
;                 f32x4 x;
;                 x.x = bflo(pw[j].x) * ri * gi.x + bflo(hw[j].x) * rstd * g.x; x.y = bfhi(pw[j].x) * ri * gi.y + bfhi(hw[j].x) * rstd * g.y;
;                 x.z = bflo(pw[j].y) * ri * gi.z + bflo(hw[j].y) * rstd * g.z; x.w = bfhi(pw[j].y) * ri * gi.w + bfhi(hw[j].y) * rstd * g.w;
;                 if (MODE == 2) *(f32x4*)(xout + (size_t)row * DM + lo4 + 256 * j) = x;
;                 else ss2 += x.x * x.x + x.y * x.y + x.z * x.z + x.w * x.w;
;                 if (j & 1) __builtin_amdgcn_sched_barrier(0); }
	v_pk_mul_f32 v[164:165], v[212:213], v[200:201]
	v_pk_mul_f32 v[166:167], v[214:215], v[202:203]
	v_pk_fma_f32 v[164:165], v[196:197], v[216:217], v[164:165]
	v_pk_fma_f32 v[166:167], v[198:199], v[218:219], v[166:167]
	v_pk_fma_f32 v[234:235], v[164:165], v[164:165], v[234:235]
	v_pk_fma_f32 v[234:235], v[166:167], v[166:167], v[234:235]
	ds_read_b128 v[196:199], v71 offset:10240
	ds_read_b128 v[200:203], v71 offset:43008
	v_lshlrev_b32_e32 v212, 16, v26
	v_and_b32_e32 v213, 0xffff0000, v26
	v_lshlrev_b32_e32 v214, 16, v27
	v_and_b32_e32 v215, 0xffff0000, v27
	v_lshlrev_b32_e32 v216, 16, v28
	v_and_b32_e32 v217, 0xffff0000, v28
	v_lshlrev_b32_e32 v218, 16, v29
	v_and_b32_e32 v219, 0xffff0000, v29
	v_pk_mul_f32 v[212:213], v[228:229], v[212:213]
	v_pk_mul_f32 v[214:215], v[228:229], v[214:215]
	v_pk_mul_f32 v[216:217], v[230:231], v[216:217]
	v_pk_mul_f32 v[218:219], v[230:231], v[218:219]
	s_waitcnt lgkmcnt(2)
	v_pk_mul_f32 v[168:169], v[212:213], v[208:209]
	v_pk_mul_f32 v[170:171], v[214:215], v[210:211]
	v_pk_fma_f32 v[168:169], v[204:205], v[216:217], v[168:169]
	v_pk_fma_f32 v[170:171], v[206:207], v[218:219], v[170:171]
	v_pk_fma_f32 v[234:235], v[168:169], v[168:169], v[234:235]
	v_pk_fma_f32 v[234:235], v[170:171], v[170:171], v[234:235]
	ds_read_b128 v[204:207], v71 offset:11264
	ds_read_b128 v[208:211], v71 offset:44032
	v_lshlrev_b32_e32 v212, 16, v22
	v_and_b32_e32 v213, 0xffff0000, v22
	v_lshlrev_b32_e32 v214, 16, v23
	v_and_b32_e32 v215, 0xffff0000, v23
	v_lshlrev_b32_e32 v216, 16, v24
	v_and_b32_e32 v217, 0xffff0000, v24
	v_lshlrev_b32_e32 v218, 16, v25
	v_and_b32_e32 v219, 0xffff0000, v25
	v_pk_mul_f32 v[212:213], v[228:229], v[212:213]
	v_pk_mul_f32 v[214:215], v[228:229], v[214:215]
	v_pk_mul_f32 v[216:217], v[230:231], v[216:217]
	v_pk_mul_f32 v[218:219], v[230:231], v[218:219]
	s_waitcnt lgkmcnt(2)
	v_pk_mul_f32 v[172:173], v[212:213], v[200:201]
	v_pk_mul_f32 v[174:175], v[214:215], v[202:203]
	v_pk_fma_f32 v[172:173], v[196:197], v[216:217], v[172:173]
	v_pk_fma_f32 v[174:175], v[198:199], v[218:219], v[174:175]
	v_pk_fma_f32 v[234:235], v[172:173], v[172:173], v[234:235]
	v_pk_fma_f32 v[234:235], v[174:175], v[174:175], v[234:235]
	ds_read_b128 v[196:199], v71 offset:12288
	ds_read_b128 v[200:203], v71 offset:45056
	v_lshlrev_b32_e32 v212, 16, v18
	v_and_b32_e32 v213, 0xffff0000, v18
	v_lshlrev_b32_e32 v214, 16, v19
	v_and_b32_e32 v215, 0xffff0000, v19
	v_lshlrev_b32_e32 v216, 16, v20
	v_and_b32_e32 v217, 0xffff0000, v20
	v_lshlrev_b32_e32 v218, 16, v21
	v_and_b32_e32 v219, 0xffff0000, v21
	v_pk_mul_f32 v[212:213], v[228:229], v[212:213]
	v_pk_mul_f32 v[214:215], v[228:229], v[214:215]
	v_pk_mul_f32 v[216:217], v[230:231], v[216:217]
	v_pk_mul_f32 v[218:219], v[230:231], v[218:219]
	s_waitcnt lgkmcnt(2)
	v_pk_mul_f32 v[176:177], v[212:213], v[208:209]
	v_pk_mul_f32 v[178:179], v[214:215], v[210:211]
	v_pk_fma_f32 v[176:177], v[204:205], v[216:217], v[176:177]
	v_pk_fma_f32 v[178:179], v[206:207], v[218:219], v[178:179]
	v_pk_fma_f32 v[234:235], v[176:177], v[176:177], v[234:235]
	v_pk_fma_f32 v[234:235], v[178:179], v[178:179], v[234:235]
	ds_read_b128 v[204:207], v71 offset:13312
	ds_read_b128 v[208:211], v71 offset:46080
	v_lshlrev_b32_e32 v212, 16, v14
	v_and_b32_e32 v213, 0xffff0000, v14
	v_lshlrev_b32_e32 v214, 16, v15
	v_and_b32_e32 v215, 0xffff0000, v15
	v_lshlrev_b32_e32 v216, 16, v16
	v_and_b32_e32 v217, 0xffff0000, v16
	v_lshlrev_b32_e32 v218, 16, v17
	v_and_b32_e32 v219, 0xffff0000, v17
	v_pk_mul_f32 v[212:213], v[228:229], v[212:213]
	v_pk_mul_f32 v[214:215], v[228:229], v[214:215]
	v_pk_mul_f32 v[216:217], v[230:231], v[216:217]
	v_pk_mul_f32 v[218:219], v[230:231], v[218:219]
	s_waitcnt lgkmcnt(2)
; #define LAS __attribute__((address_space(3)))
; __device__ __forceinline__ float bflo(unsigned w) { return __uint_as_float(w << 16); }
; __device__ __forceinline__ float bfhi(unsigned w) { return __uint_as_float(w & 0xffff0000u); }
; template <int MODE> ...
;     ...
;             for (int j = 0; j < 16; ++j) { const f32x4 g = *(const LAS f32x4*)(GP + lo4 + 256 * j), gi = *(const LAS f32x4*)(GI + lo4 + 256 * j);
;                 f32x4 x;
;                 x.x = bflo(pw[j].x) * ri * gi.x + bflo(hw[j].x) * rstd * g.x; x.y = bfhi(pw[j].x) * ri * gi.y + bfhi(hw[j].x) * rstd * g.y;
;                 x.z = bflo(pw[j].y) * ri * gi.z + bflo(hw[j].y) * rstd * g.z; x.w = bfhi(pw[j].y) * ri * gi.w + bfhi(hw[j].y) * rstd * g.w;
;                 if (MODE == 2) *(f32x4*)(xout + (size_t)row * DM + lo4 + 256 * j) = x;
;                 else ss2 += x.x * x.x + x.y * x.y + x.z * x.z + x.w * x.w;
;                 if (j & 1) __builtin_amdgcn_sched_barrier(0); }
;             if (MODE == 1) {
;                 const float rstd2 = rsqrtf(wave_sum(ss2) * (1.f / DM) + EPS);
;                 if (lane == 0) rs_out[row] = rstd2;
	v_pk_mul_f32 v[180:181], v[212:213], v[200:201]
	v_pk_mul_f32 v[182:183], v[214:215], v[202:203]
	v_pk_fma_f32 v[180:181], v[196:197], v[216:217], v[180:181]
	v_pk_fma_f32 v[182:183], v[198:199], v[218:219], v[182:183]
	v_pk_fma_f32 v[234:235], v[180:181], v[180:181], v[234:235]
	v_pk_fma_f32 v[234:235], v[182:183], v[182:183], v[234:235]
	ds_read_b128 v[196:199], v71 offset:14336
	ds_read_b128 v[200:203], v71 offset:47104
	v_lshlrev_b32_e32 v212, 16, v10
	v_and_b32_e32 v213, 0xffff0000, v10
	v_lshlrev_b32_e32 v214, 16, v11
	v_and_b32_e32 v215, 0xffff0000, v11
	v_lshlrev_b32_e32 v216, 16, v12
	v_and_b32_e32 v217, 0xffff0000, v12
	v_lshlrev_b32_e32 v218, 16, v13
	v_and_b32_e32 v219, 0xffff0000, v13
	v_pk_mul_f32 v[212:213], v[228:229], v[212:213]
	v_pk_mul_f32 v[214:215], v[228:229], v[214:215]
	v_pk_mul_f32 v[216:217], v[230:231], v[216:217]
	v_pk_mul_f32 v[218:219], v[230:231], v[218:219]
	s_waitcnt lgkmcnt(2)
	v_pk_mul_f32 v[184:185], v[212:213], v[208:209]
	v_pk_mul_f32 v[186:187], v[214:215], v[210:211]
	v_pk_fma_f32 v[184:185], v[204:205], v[216:217], v[184:185]
	v_pk_fma_f32 v[186:187], v[206:207], v[218:219], v[186:187]
	v_pk_fma_f32 v[234:235], v[184:185], v[184:185], v[234:235]
	v_pk_fma_f32 v[234:235], v[186:187], v[186:187], v[234:235]
	ds_read_b128 v[204:207], v71 offset:15360
	ds_read_b128 v[208:211], v71 offset:48128
	v_lshlrev_b32_e32 v212, 16, v6
	v_and_b32_e32 v213, 0xffff0000, v6
	v_lshlrev_b32_e32 v214, 16, v7
	v_and_b32_e32 v215, 0xffff0000, v7
	v_lshlrev_b32_e32 v216, 16, v8
	v_and_b32_e32 v217, 0xffff0000, v8
	v_lshlrev_b32_e32 v218, 16, v9
	v_and_b32_e32 v219, 0xffff0000, v9
	v_pk_mul_f32 v[212:213], v[228:229], v[212:213]
	v_pk_mul_f32 v[214:215], v[228:229], v[214:215]
	v_pk_mul_f32 v[216:217], v[230:231], v[216:217]
	v_pk_mul_f32 v[218:219], v[230:231], v[218:219]
	s_waitcnt lgkmcnt(2)
	v_pk_mul_f32 v[188:189], v[212:213], v[200:201]
	v_pk_mul_f32 v[190:191], v[214:215], v[202:203]
	v_pk_fma_f32 v[188:189], v[196:197], v[216:217], v[188:189]
	v_pk_fma_f32 v[190:191], v[198:199], v[218:219], v[190:191]
	v_pk_fma_f32 v[234:235], v[188:189], v[188:189], v[234:235]
	v_pk_fma_f32 v[234:235], v[190:191], v[190:191], v[234:235]
	v_lshlrev_b32_e32 v212, 16, v2
	v_and_b32_e32 v213, 0xffff0000, v2
	v_lshlrev_b32_e32 v214, 16, v3
	v_and_b32_e32 v215, 0xffff0000, v3
	v_lshlrev_b32_e32 v216, 16, v4
	v_and_b32_e32 v217, 0xffff0000, v4
	v_lshlrev_b32_e32 v218, 16, v5
	v_and_b32_e32 v219, 0xffff0000, v5
	v_pk_mul_f32 v[212:213], v[228:229], v[212:213]
	v_pk_mul_f32 v[214:215], v[228:229], v[214:215]
	v_pk_mul_f32 v[216:217], v[230:231], v[216:217]
	v_pk_mul_f32 v[218:219], v[230:231], v[218:219]
	s_waitcnt lgkmcnt(0)
	v_pk_mul_f32 v[192:193], v[212:213], v[208:209]
	v_pk_mul_f32 v[194:195], v[214:215], v[210:211]
	v_pk_fma_f32 v[192:193], v[204:205], v[216:217], v[192:193]
	v_pk_fma_f32 v[194:195], v[206:207], v[218:219], v[194:195]
	v_pk_fma_f32 v[234:235], v[192:193], v[192:193], v[234:235]
	v_pk_fma_f32 v[234:235], v[194:195], v[194:195], v[234:235]
	v_add_f32_e32 v77, v234, v235
	s_nop 1
	v_add_f32_dpp v77, v77, v77 quad_perm:[1,0,3,2] row_mask:0xf bank_mask:0xf
	s_nop 1
	v_add_f32_dpp v77, v77, v77 quad_perm:[2,3,0,1] row_mask:0xf bank_mask:0xf
	s_nop 1
	v_add_f32_dpp v77, v77, v77 row_half_mirror row_mask:0xf bank_mask:0xf
	s_nop 1
	v_add_f32_dpp v77, v77, v77 row_mirror row_mask:0xf bank_mask:0xf
	s_nop 1
	v_readlane_b32 s98, v77, 0
	v_readlane_b32 s99, v77, 16
	v_readlane_b32 s100, v77, 32
	v_readlane_b32 s101, v77, 48
	s_nop 1
	v_mov_b32_e32 v70, s98
	v_add_f32_e32 v70, s99, v70
	v_add_f32_e32 v70, s100, v70
	v_add_f32_e32 v70, s101, v70
	v_fmamk_f32 v70, v70, 0x39800000, v99
	v_mul_f32_e32 v72, 0x4b800000, v70
	v_cmp_gt_f32_e32 vcc, s66, v70
	s_nop 1
	v_cndmask_b32_e32 v70, v70, v72, vcc
	v_rsq_f32_e32 v70, v70
	s_nop 0
	v_mul_f32_e32 v72, 0x45800000, v70
	v_cndmask_b32_e32 v70, v70, v72, vcc
	s_and_saveexec_b64 s[6:7], s[4:5]
	s_cbranch_execz .LBB0_775
	global_store_dword v98, v70, s[62:63]
	s_branch .LBB0_775

; __device__ __forceinline__ float bflo(unsigned w) { return __uint_as_float(w << 16); }
; __device__ __forceinline__ float bfhi(unsigned w) { return __uint_as_float(w & 0xffff0000u); }
; template <int MODE> ...
;     ...
;             const bf16* pr = xn + (size_t)row * DM; bf16* pw_out = xn_out + (size_t)row * DM; const bf16* hr = hb + (size_t)row * DM;
;             v2u pw[16], hw[16]; float ss = 0.f;
; #pragma unroll
;             for (int j = 0; j < 16; ++j) { pw[j] = *(const v2u*)(pr + lo4 + 256 * j); hw[j] = *(const v2u*)(hr + lo4 + 256 * j); }
;             const float ri = 1.f / rs[row];
; #pragma unroll
;             for (int j = 0; j < 16; ++j) { const float a = bflo(hw[j].x), b = bfhi(hw[j].x), c = bflo(hw[j].y), d = bfhi(hw[j].y); ss += a * a + b * b + c * c + d * d; }
.LBB0_1119:
	v_lshl_add_u64 v[68:69], v[0:1], 0, s[12:13]
	v_add_co_u32_e32 v26, vcc, 0x3000000, v68
	s_mov_b64 s[6:7], vcc
	v_add_co_u32_e32 v2, vcc, 0x7000000, v68
	s_add_u32 s62, s64, s12
	s_nop 0
	v_addc_co_u32_e32 v3, vcc, 0, v69, vcc
	global_load_dwordx2 v[60:61], v[2:3], off
	global_load_dwordx2 v[56:57], v[2:3], off offset:512
	global_load_dwordx2 v[54:55], v[2:3], off offset:1024
	global_load_dwordx2 v[50:51], v[2:3], off offset:1536
	global_load_dwordx2 v[46:47], v[2:3], off offset:2048
	global_load_dwordx2 v[44:45], v[2:3], off offset:2560
	v_add_co_u32_e32 v4, vcc, s39, v68
	s_addc_u32 s63, s65, s13
	s_nop 0
	v_addc_co_u32_e32 v5, vcc, 0, v69, vcc
	v_add_co_u32_e32 v38, vcc, s41, v68
	s_waitcnt vmcnt(5)
	v_lshlrev_b32_e32 v70, 16, v61
	v_addc_co_u32_e32 v39, vcc, 0, v69, vcc
	v_addc_co_u32_e64 v27, vcc, 0, v69, s[6:7]
	global_load_dwordx2 v[40:41], v[2:3], off offset:3072
	global_load_dwordx2 v[32:33], v[4:5], off
	global_load_dwordx2 v[28:29], v[4:5], off offset:512
	global_load_dwordx2 v[22:23], v[4:5], off offset:1024
	global_load_dwordx2 v[18:19], v[4:5], off offset:1536
	global_load_dwordx2 v[34:35], v[38:39], off
	global_load_dwordx2 v[30:31], v[38:39], off offset:512
	global_load_dwordx2 v[24:25], v[38:39], off offset:1024
	global_load_dwordx2 v[20:21], v[38:39], off offset:1536
	global_load_dwordx2 v[36:37], v[2:3], off offset:3584
	global_load_dwordx2 v[14:15], v[4:5], off offset:2048
	global_load_dwordx2 v[10:11], v[4:5], off offset:2560
	global_load_dwordx2 v[6:7], v[4:5], off offset:3072
	s_nop 0
	global_load_dwordx2 v[2:3], v[4:5], off offset:3584
	global_load_dwordx2 v[16:17], v[38:39], off offset:2048
	global_load_dwordx2 v[12:13], v[38:39], off offset:2560
	global_load_dwordx2 v[8:9], v[38:39], off offset:3072
	s_nop 0
	global_load_dwordx2 v[4:5], v[38:39], off offset:3584
	global_load_dword v78, v79, s[62:63]
	global_load_dwordx2 v[66:67], v[26:27], off
	global_load_dwordx2 v[64:65], v[26:27], off offset:512
	global_load_dwordx2 v[62:63], v[26:27], off offset:1024
	global_load_dwordx2 v[58:59], v[26:27], off offset:1536
	global_load_dwordx2 v[52:53], v[26:27], off offset:2048
	global_load_dwordx2 v[48:49], v[26:27], off offset:2560
	global_load_dwordx2 v[42:43], v[26:27], off offset:3072
	global_load_dwordx2 v[38:39], v[26:27], off offset:3584
	v_and_b32_e32 v27, 0xffff0000, v60
	s_waitcnt vmcnt(31)
	v_and_b32_e32 v74, 0xffff0000, v56
	v_lshlrev_b32_e32 v26, 16, v60
	v_lshlrev_b32_e32 v73, 16, v56
	v_mul_f32_e32 v27, v27, v27
	v_mul_f32_e32 v74, v74, v74
	v_lshlrev_b32_e32 v75, 16, v57
	s_waitcnt vmcnt(30)
	v_and_b32_e32 v80, 0xffff0000, v54
	v_fmac_f32_e32 v27, v26, v26
	v_fmac_f32_e32 v74, v73, v73
	v_and_b32_e32 v72, 0xffff0000, v61
	v_and_b32_e32 v76, 0xffff0000, v57
	v_lshlrev_b32_e32 v77, 16, v54
	s_waitcnt vmcnt(29)
	v_and_b32_e32 v84, 0xffff0000, v50
	s_waitcnt vmcnt(28)
	v_and_b32_e32 v88, 0xffff0000, v46
	v_mul_f32_e32 v80, v80, v80
	v_fmac_f32_e32 v27, v70, v70
	v_fmac_f32_e32 v74, v75, v75
	v_lshlrev_b32_e32 v81, 16, v55
	v_lshlrev_b32_e32 v83, 16, v50
	v_lshlrev_b32_e32 v87, 16, v46
	v_mul_f32_e32 v84, v84, v84
	v_fmac_f32_e32 v80, v77, v77
	v_fmac_f32_e32 v27, v72, v72
	v_fmac_f32_e32 v74, v76, v76
	v_mul_f32_e32 v72, v88, v88
	v_and_b32_e32 v82, 0xffff0000, v55
	v_lshlrev_b32_e32 v85, 16, v51
	v_fmac_f32_e32 v84, v83, v83
	v_fmac_f32_e32 v80, v81, v81
	v_add_f32_e32 v26, v27, v74
	v_lshlrev_b32_e32 v27, 16, v47
	v_fmac_f32_e32 v72, v87, v87
	v_and_b32_e32 v86, 0xffff0000, v51
	v_fmac_f32_e32 v84, v85, v85
	v_fmac_f32_e32 v80, v82, v82
	v_and_b32_e32 v70, 0xffff0000, v47
	v_fmac_f32_e32 v72, v27, v27
	v_fmac_f32_e32 v84, v86, v86
	v_add_f32_e32 v26, v26, v80
	v_fmac_f32_e32 v72, v70, v70
	s_waitcnt vmcnt(27)
	v_and_b32_e32 v70, 0xffff0000, v44
	v_add_f32_e32 v26, v26, v84
	v_lshlrev_b32_e32 v27, 16, v44
	v_mul_f32_e32 v70, v70, v70
	v_add_f32_e32 v26, v26, v72
	v_lshlrev_b32_e32 v72, 16, v45
	v_fmac_f32_e32 v70, v27, v27
	v_and_b32_e32 v73, 0xffff0000, v45
	v_fmac_f32_e32 v70, v72, v72
	v_fmac_f32_e32 v70, v73, v73
	v_add_f32_e32 v26, v26, v70
	s_waitcnt vmcnt(26)
	v_and_b32_e32 v70, 0xffff0000, v40
	v_lshlrev_b32_e32 v27, 16, v40
	v_mul_f32_e32 v70, v70, v70
	v_lshlrev_b32_e32 v72, 16, v41
	v_fmac_f32_e32 v70, v27, v27
	v_and_b32_e32 v73, 0xffff0000, v41
	v_fmac_f32_e32 v70, v72, v72
	v_fmac_f32_e32 v70, v73, v73
	v_add_f32_e32 v26, v26, v70
	s_waitcnt vmcnt(17)
	v_and_b32_e32 v70, 0xffff0000, v36
	v_lshlrev_b32_e32 v27, 16, v36
	v_mul_f32_e32 v70, v70, v70
	v_lshlrev_b32_e32 v72, 16, v37
	v_fmac_f32_e32 v70, v27, v27
	v_and_b32_e32 v73, 0xffff0000, v37
	v_fmac_f32_e32 v70, v72, v72
	v_fmac_f32_e32 v70, v73, v73
	v_add_f32_e32 v26, v26, v70
	v_and_b32_e32 v70, 0xffff0000, v34
	v_lshlrev_b32_e32 v27, 16, v34
	v_mul_f32_e32 v70, v70, v70
	v_lshlrev_b32_e32 v72, 16, v35
	v_fmac_f32_e32 v70, v27, v27
	v_and_b32_e32 v73, 0xffff0000, v35
	v_fmac_f32_e32 v70, v72, v72
	v_fmac_f32_e32 v70, v73, v73
	v_add_f32_e32 v26, v26, v70
	v_and_b32_e32 v70, 0xffff0000, v30
	v_lshlrev_b32_e32 v27, 16, v30
	v_mul_f32_e32 v70, v70, v70
	v_lshlrev_b32_e32 v72, 16, v31
	v_fmac_f32_e32 v70, v27, v27
	v_and_b32_e32 v73, 0xffff0000, v31
	v_fmac_f32_e32 v70, v72, v72
	v_fmac_f32_e32 v70, v73, v73
	v_add_f32_e32 v26, v26, v70
	v_and_b32_e32 v70, 0xffff0000, v24
	v_lshlrev_b32_e32 v27, 16, v24
	v_mul_f32_e32 v70, v70, v70
	v_lshlrev_b32_e32 v72, 16, v25
	v_fmac_f32_e32 v70, v27, v27
	v_and_b32_e32 v73, 0xffff0000, v25
	v_fmac_f32_e32 v70, v72, v72
	v_fmac_f32_e32 v70, v73, v73
	v_add_f32_e32 v26, v26, v70
	v_and_b32_e32 v70, 0xffff0000, v20
	v_lshlrev_b32_e32 v27, 16, v20
	v_mul_f32_e32 v70, v70, v70
	v_lshlrev_b32_e32 v72, 16, v21
	v_fmac_f32_e32 v70, v27, v27
	v_and_b32_e32 v73, 0xffff0000, v21
	v_fmac_f32_e32 v70, v72, v72
	v_fmac_f32_e32 v70, v73, v73
	s_waitcnt vmcnt(11)
; #define LAS __attribute__((address_space(3)))
; __device__ __forceinline__ float bflo(unsigned w) { return __uint_as_float(w << 16); }
; __device__ __forceinline__ float bfhi(unsigned w) { return __uint_as_float(w & 0xffff0000u); }
; #define LAUNDER_ROW(pw, hw) do { LAUNDER8(pw, 0); LAUNDER8(pw, 8); LAUNDER8(hw, 0); LAUNDER8(hw, 8); } while (0)
; template <int MODE> ...
;     ...
;             const float ri = 1.f / rs[row];
; #pragma unroll
;             for (int j = 0; j < 16; ++j) { const float a = bflo(hw[j].x), b = bfhi(hw[j].x), c = bflo(hw[j].y), d = bfhi(hw[j].y); ss += a * a + b * b + c * c + d * d; }
;             const float rstd = rsqrtf(wave_sum(ss) * (1.f / DM) + EPS);
;             asm volatile("" ::: "memory");
;             LAUNDER_ROW(pw, hw);
;             float ss2 = 0.f;
; #pragma unroll
;             for (int j = 0; j < 16; ++j) { const f32x4 g = *(const LAS f32x4*)(GP + lo4 + 256 * j), gi = *(const LAS f32x4*)(GI + lo4 + 256 * j);
;                 f32x4 x;
;                 x.x = bflo(pw[j].x) * ri * gi.x + bflo(hw[j].x) * rstd * g.x; x.y = bfhi(pw[j].x) * ri * gi.y + bfhi(hw[j].x) * rstd * g.y;
;                 x.z = bflo(pw[j].y) * ri * gi.z + bflo(hw[j].y) * rstd * g.z; x.w = bfhi(pw[j].y) * ri * gi.w + bfhi(hw[j].y) * rstd * g.w;
;                 if (MODE == 2) *(f32x4*)(xout + (size_t)row * DM + lo4 + 256 * j) = x;
;                 else ss2 += x.x * x.x + x.y * x.y + x.z * x.z + x.w * x.w;
	v_and_b32_e32 v73, 0xffff0000, v12
	v_and_b32_e32 v72, 0xffff0000, v16
	v_add_f32_e32 v70, v26, v70
	v_lshlrev_b32_e32 v27, 16, v12
	v_lshlrev_b32_e32 v26, 16, v16
	v_pk_mul_f32 v[72:73], v[72:73], v[72:73]
	v_lshlrev_b32_e32 v75, 16, v13
	v_lshlrev_b32_e32 v74, 16, v17
	v_pk_fma_f32 v[26:27], v[26:27], v[26:27], v[72:73]
	v_and_b32_e32 v77, 0xffff0000, v13
	v_and_b32_e32 v76, 0xffff0000, v17
	v_pk_fma_f32 v[26:27], v[74:75], v[74:75], v[26:27]
	s_waitcnt vmcnt(9)
	v_and_b32_e32 v73, 0xffff0000, v4
	v_pk_fma_f32 v[26:27], v[76:77], v[76:77], v[26:27]
	v_and_b32_e32 v72, 0xffff0000, v8
	v_add_f32_e32 v26, v70, v26
	v_add_f32_e32 v70, v26, v27
	v_lshlrev_b32_e32 v27, 16, v4
	v_lshlrev_b32_e32 v26, 16, v8
	v_pk_mul_f32 v[72:73], v[72:73], v[72:73]
	v_lshlrev_b32_e32 v75, 16, v5
	v_lshlrev_b32_e32 v74, 16, v9
	v_pk_fma_f32 v[26:27], v[26:27], v[26:27], v[72:73]
	v_and_b32_e32 v77, 0xffff0000, v5
	v_and_b32_e32 v76, 0xffff0000, v9
	v_pk_fma_f32 v[26:27], v[74:75], v[74:75], v[26:27]
	s_waitcnt vmcnt(0)
	v_pk_fma_f32 v[26:27], v[76:77], v[76:77], v[26:27]
	v_div_scale_f32 v77, s[6:7], v78, v78, 1.0
	v_add_f32_e32 v26, v70, v26
	v_add_f32_e32 v26, v26, v27
	v_and_b32_e32 v27, 64, v101
	v_add_u32_e32 v27, 64, v27
	v_xor_b32_e32 v70, 1, v101
	v_cmp_lt_i32_e32 vcc, v70, v27
	v_rcp_f32_e32 v80, v77
	s_nop 0
	v_cndmask_b32_e32 v70, v101, v70, vcc
	v_lshlrev_b32_e32 v70, 2, v70
	ds_bpermute_b32 v72, v70, v26
	v_fma_f32 v81, -v77, v80, 1.0
	v_fmac_f32_e32 v80, v81, v80
	s_waitcnt lgkmcnt(0)
	v_add_f32_e32 v26, v26, v72
	v_xor_b32_e32 v72, 2, v101
	v_cmp_lt_i32_e32 vcc, v72, v27
	s_nop 1
	v_cndmask_b32_e32 v72, v101, v72, vcc
	v_lshlrev_b32_e32 v72, 2, v72
	ds_bpermute_b32 v73, v72, v26
	s_waitcnt lgkmcnt(0)
	v_add_f32_e32 v26, v26, v73
	v_xor_b32_e32 v73, 4, v101
	v_cmp_lt_i32_e32 vcc, v73, v27
	s_nop 1
	v_cndmask_b32_e32 v73, v101, v73, vcc
	v_lshlrev_b32_e32 v73, 2, v73
	ds_bpermute_b32 v74, v73, v26
	s_waitcnt lgkmcnt(0)
	v_add_f32_e32 v26, v26, v74
	v_xor_b32_e32 v74, 8, v101
	v_cmp_lt_i32_e32 vcc, v74, v27
	s_nop 1
	v_cndmask_b32_e32 v74, v101, v74, vcc
	v_lshlrev_b32_e32 v74, 2, v74
	ds_bpermute_b32 v75, v74, v26
	s_waitcnt lgkmcnt(0)
	v_add_f32_e32 v26, v26, v75
	v_xor_b32_e32 v75, 16, v101
	v_cmp_lt_i32_e32 vcc, v75, v27
	s_nop 1
	v_cndmask_b32_e32 v75, v101, v75, vcc
	v_lshlrev_b32_e32 v75, 2, v75
	ds_bpermute_b32 v76, v75, v26
	v_div_scale_f32 v81, vcc, 1.0, v78, 1.0
	v_mul_f32_e32 v82, v81, v80
	v_fma_f32 v83, -v77, v82, v81
	s_waitcnt lgkmcnt(0)
	v_add_f32_e32 v26, v26, v76
	v_xor_b32_e32 v76, 32, v101
	v_cmp_lt_i32_e64 s[6:7], v76, v27
	v_fmac_f32_e32 v82, v83, v80
	v_fma_f32 v77, -v77, v82, v81
	v_cndmask_b32_e64 v27, v101, v76, s[6:7]
	v_lshlrev_b32_e32 v76, 2, v27
	ds_bpermute_b32 v27, v76, v26
	s_waitcnt lgkmcnt(0)
	v_add_f32_e32 v26, v26, v27
	v_fmamk_f32 v26, v26, 0x39800000, v100
	v_mul_f32_e32 v27, 0x4b800000, v26
	v_cmp_gt_f32_e64 s[6:7], s66, v26
	s_nop 1
	v_cndmask_b32_e64 v26, v26, v27, s[6:7]
	v_rsq_f32_e32 v27, v26
	v_div_fmas_f32 v26, v77, v80, v82
	v_div_fixup_f32 v26, v26, v78, 1.0
	v_mul_f32_e32 v77, 0x45800000, v27
	v_cndmask_b32_e64 v27, v27, v77, s[6:7]
	v_mov_b32_e32 v228, v26
	v_mov_b32_e32 v229, v26
	v_mov_b32_e32 v230, v27
	v_mov_b32_e32 v231, v27
	ds_read_b128 v[196:199], v71
	ds_read_b128 v[200:203], v71 offset:32768
	ds_read_b128 v[204:207], v71 offset:1024
	ds_read_b128 v[208:211], v71 offset:33792
	v_lshlrev_b32_e32 v212, 16, v66
	v_and_b32_e32 v213, 0xffff0000, v66
	v_lshlrev_b32_e32 v214, 16, v67
	v_and_b32_e32 v215, 0xffff0000, v67
	v_lshlrev_b32_e32 v216, 16, v60
	v_and_b32_e32 v217, 0xffff0000, v60
	v_lshlrev_b32_e32 v218, 16, v61
	v_and_b32_e32 v219, 0xffff0000, v61
	v_pk_mul_f32 v[212:213], v[228:229], v[212:213]
	v_pk_mul_f32 v[214:215], v[228:229], v[214:215]
	v_pk_mul_f32 v[216:217], v[230:231], v[216:217]
	v_pk_mul_f32 v[218:219], v[230:231], v[218:219]
	s_waitcnt lgkmcnt(2)
	v_pk_mul_f32 v[132:133], v[212:213], v[200:201]
	v_pk_mul_f32 v[134:135], v[214:215], v[202:203]
	v_pk_fma_f32 v[132:133], v[196:197], v[216:217], v[132:133]
	v_pk_fma_f32 v[134:135], v[198:199], v[218:219], v[134:135]
	v_pk_mul_f32 v[234:235], v[132:133], v[132:133]
	v_pk_fma_f32 v[234:235], v[134:135], v[134:135], v[234:235]
	ds_read_b128 v[196:199], v71 offset:2048
	ds_read_b128 v[200:203], v71 offset:34816
	v_lshlrev_b32_e32 v212, 16, v64
	v_and_b32_e32 v213, 0xffff0000, v64
	v_lshlrev_b32_e32 v214, 16, v65
	v_and_b32_e32 v215, 0xffff0000, v65
	v_lshlrev_b32_e32 v216, 16, v56
	v_and_b32_e32 v217, 0xffff0000, v56
	v_lshlrev_b32_e32 v218, 16, v57
	v_and_b32_e32 v219, 0xffff0000, v57
	v_pk_mul_f32 v[212:213], v[228:229], v[212:213]
	v_pk_mul_f32 v[214:215], v[228:229], v[214:215]
	v_pk_mul_f32 v[216:217], v[230:231], v[216:217]
	v_pk_mul_f32 v[218:219], v[230:231], v[218:219]
	s_waitcnt lgkmcnt(2)
	v_pk_mul_f32 v[136:137], v[212:213], v[208:209]
	v_pk_mul_f32 v[138:139], v[214:215], v[210:211]
	v_pk_fma_f32 v[136:137], v[204:205], v[216:217], v[136:137]
	v_pk_fma_f32 v[138:139], v[206:207], v[218:219], v[138:139]
	v_pk_fma_f32 v[234:235], v[136:137], v[136:137], v[234:235]
	v_pk_fma_f32 v[234:235], v[138:139], v[138:139], v[234:235]
	ds_read_b128 v[204:207], v71 offset:3072
	ds_read_b128 v[208:211], v71 offset:35840
	v_lshlrev_b32_e32 v212, 16, v62
	v_and_b32_e32 v213, 0xffff0000, v62
	v_lshlrev_b32_e32 v214, 16, v63
	v_and_b32_e32 v215, 0xffff0000, v63
	v_lshlrev_b32_e32 v216, 16, v54
	v_and_b32_e32 v217, 0xffff0000, v54
	v_lshlrev_b32_e32 v218, 16, v55
	v_and_b32_e32 v219, 0xffff0000, v55
	v_pk_mul_f32 v[212:213], v[228:229], v[212:213]
	v_pk_mul_f32 v[214:215], v[228:229], v[214:215]
	v_pk_mul_f32 v[216:217], v[230:231], v[216:217]
	v_pk_mul_f32 v[218:219], v[230:231], v[218:219]
	s_waitcnt lgkmcnt(2)
; #define LAS __attribute__((address_space(3)))
; __device__ __forceinline__ float bflo(unsigned w) { return __uint_as_float(w << 16); }
; __device__ __forceinline__ float bfhi(unsigned w) { return __uint_as_float(w & 0xffff0000u); }
; template <int MODE> ...
;     ...
;             for (int j = 0; j < 16; ++j) { const f32x4 g = *(const LAS f32x4*)(GP + lo4 + 256 * j), gi = *(const LAS f32x4*)(GI + lo4 + 256 * j);
;                 f32x4 x;
;                 x.x = bflo(pw[j].x) * ri * gi.x + bflo(hw[j].x) * rstd * g.x; x.y = bfhi(pw[j].x) * ri * gi.y + bfhi(hw[j].x) * rstd * g.y;
;                 x.z = bflo(pw[j].y) * ri * gi.z + bflo(hw[j].y) * rstd * g.z; x.w = bfhi(pw[j].y) * ri * gi.w + bfhi(hw[j].y) * rstd * g.w;
;                 if (MODE == 2) *(f32x4*)(xout + (size_t)row * DM + lo4 + 256 * j) = x;
;                 else ss2 += x.x * x.x + x.y * x.y + x.z * x.z + x.w * x.w;
;                 if (j & 1) __builtin_amdgcn_sched_barrier(0); }
	v_pk_mul_f32 v[140:141], v[212:213], v[200:201]
	v_pk_mul_f32 v[142:143], v[214:215], v[202:203]
	v_pk_fma_f32 v[140:141], v[196:197], v[216:217], v[140:141]
	v_pk_fma_f32 v[142:143], v[198:199], v[218:219], v[142:143]
	v_pk_fma_f32 v[234:235], v[140:141], v[140:141], v[234:235]
	v_pk_fma_f32 v[234:235], v[142:143], v[142:143], v[234:235]
	ds_read_b128 v[196:199], v71 offset:4096
	ds_read_b128 v[200:203], v71 offset:36864
	v_lshlrev_b32_e32 v212, 16, v58
	v_and_b32_e32 v213, 0xffff0000, v58
	v_lshlrev_b32_e32 v214, 16, v59
	v_and_b32_e32 v215, 0xffff0000, v59
	v_lshlrev_b32_e32 v216, 16, v50
	v_and_b32_e32 v217, 0xffff0000, v50
	v_lshlrev_b32_e32 v218, 16, v51
	v_and_b32_e32 v219, 0xffff0000, v51
	v_pk_mul_f32 v[212:213], v[228:229], v[212:213]
	v_pk_mul_f32 v[214:215], v[228:229], v[214:215]
	v_pk_mul_f32 v[216:217], v[230:231], v[216:217]
	v_pk_mul_f32 v[218:219], v[230:231], v[218:219]
	s_waitcnt lgkmcnt(2)
	v_pk_mul_f32 v[144:145], v[212:213], v[208:209]
	v_pk_mul_f32 v[146:147], v[214:215], v[210:211]
	v_pk_fma_f32 v[144:145], v[204:205], v[216:217], v[144:145]
	v_pk_fma_f32 v[146:147], v[206:207], v[218:219], v[146:147]
	v_pk_fma_f32 v[234:235], v[144:145], v[144:145], v[234:235]
	v_pk_fma_f32 v[234:235], v[146:147], v[146:147], v[234:235]
	ds_read_b128 v[204:207], v71 offset:5120
	ds_read_b128 v[208:211], v71 offset:37888
	v_lshlrev_b32_e32 v212, 16, v52
	v_and_b32_e32 v213, 0xffff0000, v52
	v_lshlrev_b32_e32 v214, 16, v53
	v_and_b32_e32 v215, 0xffff0000, v53
	v_lshlrev_b32_e32 v216, 16, v46
	v_and_b32_e32 v217, 0xffff0000, v46
	v_lshlrev_b32_e32 v218, 16, v47
	v_and_b32_e32 v219, 0xffff0000, v47
	v_pk_mul_f32 v[212:213], v[228:229], v[212:213]
	v_pk_mul_f32 v[214:215], v[228:229], v[214:215]
	v_pk_mul_f32 v[216:217], v[230:231], v[216:217]
	v_pk_mul_f32 v[218:219], v[230:231], v[218:219]
	s_waitcnt lgkmcnt(2)
	v_pk_mul_f32 v[148:149], v[212:213], v[200:201]
	v_pk_mul_f32 v[150:151], v[214:215], v[202:203]
	v_pk_fma_f32 v[148:149], v[196:197], v[216:217], v[148:149]
	v_pk_fma_f32 v[150:151], v[198:199], v[218:219], v[150:151]
	v_pk_fma_f32 v[234:235], v[148:149], v[148:149], v[234:235]
	v_pk_fma_f32 v[234:235], v[150:151], v[150:151], v[234:235]
	ds_read_b128 v[196:199], v71 offset:6144
	ds_read_b128 v[200:203], v71 offset:38912
	v_lshlrev_b32_e32 v212, 16, v48
	v_and_b32_e32 v213, 0xffff0000, v48
	v_lshlrev_b32_e32 v214, 16, v49
	v_and_b32_e32 v215, 0xffff0000, v49
	v_lshlrev_b32_e32 v216, 16, v44
	v_and_b32_e32 v217, 0xffff0000, v44
	v_lshlrev_b32_e32 v218, 16, v45
	v_and_b32_e32 v219, 0xffff0000, v45
	v_pk_mul_f32 v[212:213], v[228:229], v[212:213]
	v_pk_mul_f32 v[214:215], v[228:229], v[214:215]
	v_pk_mul_f32 v[216:217], v[230:231], v[216:217]
	v_pk_mul_f32 v[218:219], v[230:231], v[218:219]
	s_waitcnt lgkmcnt(2)
	v_pk_mul_f32 v[152:153], v[212:213], v[208:209]
	v_pk_mul_f32 v[154:155], v[214:215], v[210:211]
	v_pk_fma_f32 v[152:153], v[204:205], v[216:217], v[152:153]
	v_pk_fma_f32 v[154:155], v[206:207], v[218:219], v[154:155]
	v_pk_fma_f32 v[234:235], v[152:153], v[152:153], v[234:235]
	v_pk_fma_f32 v[234:235], v[154:155], v[154:155], v[234:235]
	ds_read_b128 v[204:207], v71 offset:7168
	ds_read_b128 v[208:211], v71 offset:39936
	v_lshlrev_b32_e32 v212, 16, v42
	v_and_b32_e32 v213, 0xffff0000, v42
	v_lshlrev_b32_e32 v214, 16, v43
	v_and_b32_e32 v215, 0xffff0000, v43
	v_lshlrev_b32_e32 v216, 16, v40
	v_and_b32_e32 v217, 0xffff0000, v40
	v_lshlrev_b32_e32 v218, 16, v41
	v_and_b32_e32 v219, 0xffff0000, v41
	v_pk_mul_f32 v[212:213], v[228:229], v[212:213]
	v_pk_mul_f32 v[214:215], v[228:229], v[214:215]
	v_pk_mul_f32 v[216:217], v[230:231], v[216:217]
	v_pk_mul_f32 v[218:219], v[230:231], v[218:219]
	s_waitcnt lgkmcnt(2)
	v_pk_mul_f32 v[156:157], v[212:213], v[200:201]
	v_pk_mul_f32 v[158:159], v[214:215], v[202:203]
	v_pk_fma_f32 v[156:157], v[196:197], v[216:217], v[156:157]
	v_pk_fma_f32 v[158:159], v[198:199], v[218:219], v[158:159]
	v_pk_fma_f32 v[234:235], v[156:157], v[156:157], v[234:235]
	v_pk_fma_f32 v[234:235], v[158:159], v[158:159], v[234:235]
	ds_read_b128 v[196:199], v71 offset:8192
	ds_read_b128 v[200:203], v71 offset:40960
	v_lshlrev_b32_e32 v212, 16, v38
	v_and_b32_e32 v213, 0xffff0000, v38
	v_lshlrev_b32_e32 v214, 16, v39
	v_and_b32_e32 v215, 0xffff0000, v39
	v_lshlrev_b32_e32 v216, 16, v36
	v_and_b32_e32 v217, 0xffff0000, v36
	v_lshlrev_b32_e32 v218, 16, v37
	v_and_b32_e32 v219, 0xffff0000, v37
	v_pk_mul_f32 v[212:213], v[228:229], v[212:213]
	v_pk_mul_f32 v[214:215], v[228:229], v[214:215]
	v_pk_mul_f32 v[216:217], v[230:231], v[216:217]
	v_pk_mul_f32 v[218:219], v[230:231], v[218:219]
	s_waitcnt lgkmcnt(2)
	v_pk_mul_f32 v[160:161], v[212:213], v[208:209]
	v_pk_mul_f32 v[162:163], v[214:215], v[210:211]
	v_pk_fma_f32 v[160:161], v[204:205], v[216:217], v[160:161]
	v_pk_fma_f32 v[162:163], v[206:207], v[218:219], v[162:163]
	v_pk_fma_f32 v[234:235], v[160:161], v[160:161], v[234:235]
	v_pk_fma_f32 v[234:235], v[162:163], v[162:163], v[234:235]
	ds_read_b128 v[204:207], v71 offset:9216
	ds_read_b128 v[208:211], v71 offset:41984
	v_lshlrev_b32_e32 v212, 16, v32
	v_and_b32_e32 v213, 0xffff0000, v32
	v_lshlrev_b32_e32 v214, 16, v33
	v_and_b32_e32 v215, 0xffff0000, v33
	v_lshlrev_b32_e32 v216, 16, v34
	v_and_b32_e32 v217, 0xffff0000, v34
	v_lshlrev_b32_e32 v218, 16, v35
	v_and_b32_e32 v219, 0xffff0000, v35
	v_pk_mul_f32 v[212:213], v[228:229], v[212:213]
	v_pk_mul_f32 v[214:215], v[228:229], v[214:215]
	v_pk_mul_f32 v[216:217], v[230:231], v[216:217]
	v_pk_mul_f32 v[218:219], v[230:231], v[218:219]
	s_waitcnt lgkmcnt(2)
; #define LAS __attribute__((address_space(3)))
; __device__ __forceinline__ float bflo(unsigned w) { return __uint_as_float(w << 16); }
; __device__ __forceinline__ float bfhi(unsigned w) { return __uint_as_float(w & 0xffff0000u); }
; template <int MODE> ...
;     ...
;             for (int j = 0; j < 16; ++j) { const f32x4 g = *(const LAS f32x4*)(GP + lo4 + 256 * j), gi = *(const LAS f32x4*)(GI + lo4 + 256 * j);
;                 f32x4 x;
;                 x.x = bflo(pw[j].x) * ri * gi.x + bflo(hw[j].x) * rstd * g.x; x.y = bfhi(pw[j].x) * ri * gi.y + bfhi(hw[j].x) * rstd * g.y;
;                 x.z = bflo(pw[j].y) * ri * gi.z + bflo(hw[j].y) * rstd * g.z; x.w = bfhi(pw[j].y) * ri * gi.w + bfhi(hw[j].y) * rstd * g.w;
;                 if (MODE == 2) *(f32x4*)(xout + (size_t)row * DM + lo4 + 256 * j) = x;
;                 else ss2 += x.x * x.x + x.y * x.y + x.z * x.z + x.w * x.w;
;                 if (j & 1) __builtin_amdgcn_sched_barrier(0); }
	v_pk_mul_f32 v[164:165], v[212:213], v[200:201]
	v_pk_mul_f32 v[166:167], v[214:215], v[202:203]
	v_pk_fma_f32 v[164:165], v[196:197], v[216:217], v[164:165]
	v_pk_fma_f32 v[166:167], v[198:199], v[218:219], v[166:167]
	v_pk_fma_f32 v[234:235], v[164:165], v[164:165], v[234:235]
	v_pk_fma_f32 v[234:235], v[166:167], v[166:167], v[234:235]
	ds_read_b128 v[196:199], v71 offset:10240
	ds_read_b128 v[200:203], v71 offset:43008
	v_lshlrev_b32_e32 v212, 16, v28
	v_and_b32_e32 v213, 0xffff0000, v28
	v_lshlrev_b32_e32 v214, 16, v29
	v_and_b32_e32 v215, 0xffff0000, v29
	v_lshlrev_b32_e32 v216, 16, v30
	v_and_b32_e32 v217, 0xffff0000, v30
	v_lshlrev_b32_e32 v218, 16, v31
	v_and_b32_e32 v219, 0xffff0000, v31
	v_pk_mul_f32 v[212:213], v[228:229], v[212:213]
	v_pk_mul_f32 v[214:215], v[228:229], v[214:215]
	v_pk_mul_f32 v[216:217], v[230:231], v[216:217]
	v_pk_mul_f32 v[218:219], v[230:231], v[218:219]
	s_waitcnt lgkmcnt(2)
	v_pk_mul_f32 v[168:169], v[212:213], v[208:209]
	v_pk_mul_f32 v[170:171], v[214:215], v[210:211]
	v_pk_fma_f32 v[168:169], v[204:205], v[216:217], v[168:169]
	v_pk_fma_f32 v[170:171], v[206:207], v[218:219], v[170:171]
	v_pk_fma_f32 v[234:235], v[168:169], v[168:169], v[234:235]
	v_pk_fma_f32 v[234:235], v[170:171], v[170:171], v[234:235]
	ds_read_b128 v[204:207], v71 offset:11264
	ds_read_b128 v[208:211], v71 offset:44032
	v_lshlrev_b32_e32 v212, 16, v22
	v_and_b32_e32 v213, 0xffff0000, v22
	v_lshlrev_b32_e32 v214, 16, v23
	v_and_b32_e32 v215, 0xffff0000, v23
	v_lshlrev_b32_e32 v216, 16, v24
	v_and_b32_e32 v217, 0xffff0000, v24
	v_lshlrev_b32_e32 v218, 16, v25
	v_and_b32_e32 v219, 0xffff0000, v25
	v_pk_mul_f32 v[212:213], v[228:229], v[212:213]
	v_pk_mul_f32 v[214:215], v[228:229], v[214:215]
	v_pk_mul_f32 v[216:217], v[230:231], v[216:217]
	v_pk_mul_f32 v[218:219], v[230:231], v[218:219]
	s_waitcnt lgkmcnt(2)
	v_pk_mul_f32 v[172:173], v[212:213], v[200:201]
	v_pk_mul_f32 v[174:175], v[214:215], v[202:203]
	v_pk_fma_f32 v[172:173], v[196:197], v[216:217], v[172:173]
	v_pk_fma_f32 v[174:175], v[198:199], v[218:219], v[174:175]
	v_pk_fma_f32 v[234:235], v[172:173], v[172:173], v[234:235]
	v_pk_fma_f32 v[234:235], v[174:175], v[174:175], v[234:235]
	ds_read_b128 v[196:199], v71 offset:12288
	ds_read_b128 v[200:203], v71 offset:45056
	v_lshlrev_b32_e32 v212, 16, v18
	v_and_b32_e32 v213, 0xffff0000, v18
	v_lshlrev_b32_e32 v214, 16, v19
	v_and_b32_e32 v215, 0xffff0000, v19
	v_lshlrev_b32_e32 v216, 16, v20
	v_and_b32_e32 v217, 0xffff0000, v20
	v_lshlrev_b32_e32 v218, 16, v21
	v_and_b32_e32 v219, 0xffff0000, v21
	v_pk_mul_f32 v[212:213], v[228:229], v[212:213]
	v_pk_mul_f32 v[214:215], v[228:229], v[214:215]
	v_pk_mul_f32 v[216:217], v[230:231], v[216:217]
	v_pk_mul_f32 v[218:219], v[230:231], v[218:219]
	s_waitcnt lgkmcnt(2)
	v_pk_mul_f32 v[176:177], v[212:213], v[208:209]
	v_pk_mul_f32 v[178:179], v[214:215], v[210:211]
	v_pk_fma_f32 v[176:177], v[204:205], v[216:217], v[176:177]
	v_pk_fma_f32 v[178:179], v[206:207], v[218:219], v[178:179]
	v_pk_fma_f32 v[234:235], v[176:177], v[176:177], v[234:235]
	v_pk_fma_f32 v[234:235], v[178:179], v[178:179], v[234:235]
	ds_read_b128 v[204:207], v71 offset:13312
	ds_read_b128 v[208:211], v71 offset:46080
	v_lshlrev_b32_e32 v212, 16, v14
	v_and_b32_e32 v213, 0xffff0000, v14
	v_lshlrev_b32_e32 v214, 16, v15
	v_and_b32_e32 v215, 0xffff0000, v15
	v_lshlrev_b32_e32 v216, 16, v16
	v_and_b32_e32 v217, 0xffff0000, v16
	v_lshlrev_b32_e32 v218, 16, v17
	v_and_b32_e32 v219, 0xffff0000, v17
	v_pk_mul_f32 v[212:213], v[228:229], v[212:213]
	v_pk_mul_f32 v[214:215], v[228:229], v[214:215]
	v_pk_mul_f32 v[216:217], v[230:231], v[216:217]
	v_pk_mul_f32 v[218:219], v[230:231], v[218:219]
	s_waitcnt lgkmcnt(2)
; #define LAS __attribute__((address_space(3)))
; __device__ __forceinline__ float bflo(unsigned w) { return __uint_as_float(w << 16); }
; __device__ __forceinline__ float bfhi(unsigned w) { return __uint_as_float(w & 0xffff0000u); }
; template <int MODE> ...
;     ...
;             for (int j = 0; j < 16; ++j) { const f32x4 g = *(const LAS f32x4*)(GP + lo4 + 256 * j), gi = *(const LAS f32x4*)(GI + lo4 + 256 * j);
;                 f32x4 x;
;                 x.x = bflo(pw[j].x) * ri * gi.x + bflo(hw[j].x) * rstd * g.x; x.y = bfhi(pw[j].x) * ri * gi.y + bfhi(hw[j].x) * rstd * g.y;
;                 x.z = bflo(pw[j].y) * ri * gi.z + bflo(hw[j].y) * rstd * g.z; x.w = bfhi(pw[j].y) * ri * gi.w + bfhi(hw[j].y) * rstd * g.w;
;                 if (MODE == 2) *(f32x4*)(xout + (size_t)row * DM + lo4 + 256 * j) = x;
;                 else ss2 += x.x * x.x + x.y * x.y + x.z * x.z + x.w * x.w;
;                 if (j & 1) __builtin_amdgcn_sched_barrier(0); }
;             if (MODE == 1) {
;                 const float rstd2 = rsqrtf(wave_sum(ss2) * (1.f / DM) + EPS);
;                 if (lane == 0) rs_out[row] = rstd2;
	v_pk_mul_f32 v[180:181], v[212:213], v[200:201]
	v_pk_mul_f32 v[182:183], v[214:215], v[202:203]
	v_pk_fma_f32 v[180:181], v[196:197], v[216:217], v[180:181]
	v_pk_fma_f32 v[182:183], v[198:199], v[218:219], v[182:183]
	v_pk_fma_f32 v[234:235], v[180:181], v[180:181], v[234:235]
	v_pk_fma_f32 v[234:235], v[182:183], v[182:183], v[234:235]
	ds_read_b128 v[196:199], v71 offset:14336
	ds_read_b128 v[200:203], v71 offset:47104
	v_lshlrev_b32_e32 v212, 16, v10
	v_and_b32_e32 v213, 0xffff0000, v10
	v_lshlrev_b32_e32 v214, 16, v11
	v_and_b32_e32 v215, 0xffff0000, v11
	v_lshlrev_b32_e32 v216, 16, v12
	v_and_b32_e32 v217, 0xffff0000, v12
	v_lshlrev_b32_e32 v218, 16, v13
	v_and_b32_e32 v219, 0xffff0000, v13
	v_pk_mul_f32 v[212:213], v[228:229], v[212:213]
	v_pk_mul_f32 v[214:215], v[228:229], v[214:215]
	v_pk_mul_f32 v[216:217], v[230:231], v[216:217]
	v_pk_mul_f32 v[218:219], v[230:231], v[218:219]
	s_waitcnt lgkmcnt(2)
	v_pk_mul_f32 v[184:185], v[212:213], v[208:209]
	v_pk_mul_f32 v[186:187], v[214:215], v[210:211]
	v_pk_fma_f32 v[184:185], v[204:205], v[216:217], v[184:185]
	v_pk_fma_f32 v[186:187], v[206:207], v[218:219], v[186:187]
	v_pk_fma_f32 v[234:235], v[184:185], v[184:185], v[234:235]
	v_pk_fma_f32 v[234:235], v[186:187], v[186:187], v[234:235]
	ds_read_b128 v[204:207], v71 offset:15360
	ds_read_b128 v[208:211], v71 offset:48128
	v_lshlrev_b32_e32 v212, 16, v6
	v_and_b32_e32 v213, 0xffff0000, v6
	v_lshlrev_b32_e32 v214, 16, v7
	v_and_b32_e32 v215, 0xffff0000, v7
	v_lshlrev_b32_e32 v216, 16, v8
	v_and_b32_e32 v217, 0xffff0000, v8
	v_lshlrev_b32_e32 v218, 16, v9
	v_and_b32_e32 v219, 0xffff0000, v9
	v_pk_mul_f32 v[212:213], v[228:229], v[212:213]
	v_pk_mul_f32 v[214:215], v[228:229], v[214:215]
	v_pk_mul_f32 v[216:217], v[230:231], v[216:217]
	v_pk_mul_f32 v[218:219], v[230:231], v[218:219]
	s_waitcnt lgkmcnt(2)
	v_pk_mul_f32 v[188:189], v[212:213], v[200:201]
	v_pk_mul_f32 v[190:191], v[214:215], v[202:203]
	v_pk_fma_f32 v[188:189], v[196:197], v[216:217], v[188:189]
	v_pk_fma_f32 v[190:191], v[198:199], v[218:219], v[190:191]
	v_pk_fma_f32 v[234:235], v[188:189], v[188:189], v[234:235]
	v_pk_fma_f32 v[234:235], v[190:191], v[190:191], v[234:235]
	v_lshlrev_b32_e32 v212, 16, v2
	v_and_b32_e32 v213, 0xffff0000, v2
	v_lshlrev_b32_e32 v214, 16, v3
	v_and_b32_e32 v215, 0xffff0000, v3
	v_lshlrev_b32_e32 v216, 16, v4
	v_and_b32_e32 v217, 0xffff0000, v4
	v_lshlrev_b32_e32 v218, 16, v5
	v_and_b32_e32 v219, 0xffff0000, v5
	v_pk_mul_f32 v[212:213], v[228:229], v[212:213]
	v_pk_mul_f32 v[214:215], v[228:229], v[214:215]
	v_pk_mul_f32 v[216:217], v[230:231], v[216:217]
	v_pk_mul_f32 v[218:219], v[230:231], v[218:219]
	s_waitcnt lgkmcnt(0)
	v_pk_mul_f32 v[192:193], v[212:213], v[208:209]
	v_pk_mul_f32 v[194:195], v[214:215], v[210:211]
	v_pk_fma_f32 v[192:193], v[204:205], v[216:217], v[192:193]
	v_pk_fma_f32 v[194:195], v[206:207], v[218:219], v[194:195]
	v_pk_fma_f32 v[234:235], v[192:193], v[192:193], v[234:235]
	v_pk_fma_f32 v[234:235], v[194:195], v[194:195], v[234:235]
	v_add_f32_e32 v77, v234, v235
	s_nop 1
	v_add_f32_dpp v77, v77, v77 quad_perm:[1,0,3,2] row_mask:0xf bank_mask:0xf
	s_nop 1
	v_add_f32_dpp v77, v77, v77 quad_perm:[2,3,0,1] row_mask:0xf bank_mask:0xf
	s_nop 1
	v_add_f32_dpp v77, v77, v77 row_half_mirror row_mask:0xf bank_mask:0xf
	s_nop 1
	v_add_f32_dpp v77, v77, v77 row_mirror row_mask:0xf bank_mask:0xf
	s_nop 1
	v_readlane_b32 s98, v77, 0
	v_readlane_b32 s99, v77, 16
	v_readlane_b32 s100, v77, 32
	v_readlane_b32 s101, v77, 48
	s_nop 1
	v_mov_b32_e32 v70, s98
	v_add_f32_e32 v70, s99, v70
	v_add_f32_e32 v70, s100, v70
	v_add_f32_e32 v70, s101, v70
	v_fmamk_f32 v70, v70, 0x39800000, v100
	v_mul_f32_e32 v72, 0x4b800000, v70
	v_cmp_gt_f32_e32 vcc, s66, v70
	s_nop 1
	v_cndmask_b32_e32 v70, v70, v72, vcc
	v_rsq_f32_e32 v70, v70
	s_nop 0
	v_mul_f32_e32 v72, 0x45800000, v70
	v_cndmask_b32_e32 v70, v70, v72, vcc
	s_and_saveexec_b64 s[6:7], s[4:5]
	s_cbranch_execz .LBB0_1118
	global_store_dword v79, v70, s[62:63]
	s_branch .LBB0_1118
